# NA: lanes fetching the always-masked 8-column key group of edge query groups (j=0,3) alias the neighbouring live group (K and V): 25% fewer lines for half the waves; token-major QK layout
# baseline (speedup 1.0000x reference)
; __device__ __forceinline__ u32x4v pack8(const f32x4& a, const f32x4& b) { u32x4v w; w.x = cvt_pk_bf16(a[0], a[1]); w.y = cvt_pk_bf16(a[2], a[3]); w.z = cvt_pk_bf16(b[0], b[1]); w.w = cvt_pk_bf16(b[2], b[3]); return w; }
; #define PG8_STAGE(bufoff, gbase, voff) do { _Pragma("unroll") for (int _i = 0; _i < 2; ++_i) \
;         __builtin_amdgcn_global_load_lds((const unsigned*)((const char*)(gbase) + (voff)[_i]), (PG8_LAS unsigned*)(lds + (bufoff) + ldsw + _i * 8192), 16, 0, 0); } while (0)
; #define PG8_WAIT_V(n) asm volatile("s_waitcnt vmcnt(" #n ")" ::: "memory")
; #define PG8_BAR __builtin_amdgcn_s_barrier()
;     __device__ __forceinline__ void operator()(const f32x4 (&acc)[2][2][4][2], const Unit& u, int wr, int wc, int fr, int fq) const {
;     ...
;             for (int m = 0; m < 4; ++m) { const int r = row0 + ai * HALF + m * 16; const float rs = rstd[r]; bf16_t* rowp = O + (size_t)r * ldc + col0;
; #pragma unroll
;                 for (int bj = 0; bj < 2; ++bj) { const f32x4 v0 = acc[ai][bj][m][0] * rs + bv[bj][0], v1 = acc[ai][bj][m][1] * rs + bv[bj][1];
;                     const int c = col0 + bj * HALF;
;                     (void)rowp; *(u32x4v*)(O + (((size_t)(c >> 6) * 2 + ((c >> 5) & 1)) * 32768 + r) * 32 + (c & 31)) = pack8(v0, v1); } }
; template <class Epi, class Sched, bool ALIGN_EPI = false, bool SP2 = false>
; __device__ __forceinline__ void gemm_phase(PG8_LAS unsigned char* lds, const Gemm g, const Sched& S, const Epi& E) {
;     ...
;         PG8_STAGE(PG8_SB(0, 0), cB, voffB); PG8_STAGE(PG8_SB(0, 1), cB + hstep, voffB); PG8_STAGE(PG8_SA(0, 0), cA, voffA); PG8_STAGE(PG8_SA(0, 1), cA + hstep, voffA);
;         if (wr == 1) PG8_BAR;
;         PG8_WAIT_V(2); PG8_BAR;
;         PG8_STAGE(PG8_SB(1, 0), cB + kstep, voffB); PG8_STAGE(PG8_SA(1, 0), cA + kstep, voffA); PG8_STAGE(PG8_SB(1, 1), cB + hstep + kstep, voffB);
;         PG8_WAIT_V(6); PG8_BAR;
.LBB0_804:
	s_mov_b64 s[16:17], 0x80
	s_and_b32 s19, s1, 3
	s_add_i32 m0, s46, 0x18000
	v_lshl_add_u64 v[6:7], v[6:7], 0, s[16:17]
	s_lshl_b32 s26, s18, 13
	s_lshl_b32 s50, s19, 5
	global_load_lds_dwordx4 v[6:7], off
	v_lshl_add_u64 v[4:5], v[4:5], 0, s[16:17]
	s_add_i32 m0, s46, 0x1a000
	s_add_i32 s51, s46, 0x8000
	s_add_i32 s52, s46, 0xa000
	global_load_lds_dwordx4 v[4:5], off
	v_lshl_add_u64 v[0:1], v[0:1], 0, s[16:17]
	s_mov_b32 m0, s51
	s_add_u32 s20, s6, 0x40080
	global_load_lds_dwordx4 v[0:1], off
	v_lshl_add_u64 v[0:1], v[2:3], 0, s[16:17]
	s_mov_b32 m0, s52
	s_addc_u32 s21, s7, 0
	global_load_lds_dwordx4 v[0:1], off
	s_add_i32 m0, s46, 0x1c000
	v_lshl_add_u64 v[0:1], s[20:21], 0, v[148:149]
	global_load_lds_dwordx4 v[0:1], off
	v_lshl_add_u64 v[0:1], s[20:21], 0, v[152:153]
	s_add_i32 m0, s46, 0x1e000
	v_lshlrev_b32_e32 v2, 11, v170
	global_load_lds_dwordx4 v[0:1], off
	s_waitcnt vmcnt(8)
	s_barrier
	v_lshlrev_b32_e32 v1, 2, v145
	v_lshl_or_b32 v0, v145, 6, v172
	v_and_b32_e32 v1, 32, v1
	v_bitop3_b32 v0, v0, s26, v1 bitop3:0xde
	v_lshlrev_b32_e32 v1, 8, v221
	v_and_b32_e32 v1, 0x38000, v1
	v_or3_b32 v1, v168, v1, v2
	v_add_u32_e32 v156, v1, v169
	v_lshlrev_b32_e32 v1, 4, v171
	s_waitcnt vmcnt(6)
	s_cmpk_lt_u32 s12, 0x100
	v_and_b32_e32 v1, 0x78000, v1
	s_sext_i32_i8 s35, s0
	v_lshl_or_b32 v174, s18, 6, v145
	v_lshl_or_b32 v175, s19, 12, v173
	s_cselect_b64 s[18:19], -1, 0
	s_lshl_b32 s0, s1, 15
	v_or3_b32 v1, v168, v1, v2
	s_add_i32 s55, 0, 0x10000
	s_add_i32 s56, 0, 0x14000
	s_and_b32 s12, s0, 0x8000
	s_ashr_i32 s53, s74, 31
	s_mov_b32 s54, s74
	v_mov_b32_e32 v157, v155
	v_add_u32_e32 v158, v1, v169
	v_mov_b32_e32 v159, v155
	v_mov_b64_e32 v[160:161], 0x400
	v_mov_b64_e32 v[162:163], 0x3ff
	v_add_u32_e32 v176, s55, v175
	v_add_u32_e32 v177, s56, v175
	v_add_u32_e32 v178, 0, v0
	v_lshlrev_b32_e32 v154, 1, v144
	s_mov_b32 s57, s13
	s_barrier
	s_branch .LBB0_807

; #define LAS __attribute__((address_space(3)))
; __device__ __forceinline__ void na_phase(const Frame& F, const bf16* QH, const bf16* VB, const float* rpb, bf16* U) {
;     ...
;     LAS float* RP = (LAS float*)F.lds;
;     for (int i = F.tid; i < 16 * 465; i += 512) RP[i] = rpb[i];
;     __syncthreads();
;     const int lane = F.lane, n = lane & 15, q4 = lane >> 4;
;     const int vcu = (F.G % 8 == 0) ? (F.bid % 8) * (F.G / 8) + F.bid / 8 : F.bid;
;     for (int br = vcu; br < MB * 256; br += F.G) {
;         const int b = br >> 8, r = br & 255;
;         const int rs = min(max(r - 4, 0), 248);
; #pragma unroll 1
;         for (int it = 0; it < 8; ++it) {
;             const int hj = it * 8 + F.wave, h = hj >> 2, j = hj & 3;
;             const int c0 = (j == 0) ? 0 : (j == 1) ? 8 : (j == 2) ? 24 : 32;
;             const int qcol = 16 * j + n, cs = min(max(qcol - 8, 0), 48);
;             const size_t tokq = (size_t)b * SEQL + r * 64 + qcol;
;             bf16x8 qf[2];
; #pragma unroll
;             for (int ks = 0; ks < 2; ++ks) qf[ks] = *(const bf16x8*)(QH + (((size_t)h * 2 + ks) * MTOK + tokq) * 32 + q4 * 8);
;             f32x4 acc[16];
; #pragma unroll
;             for (int blk = 0; blk < 16; ++blk) { const int i = blk >> 1, hf = blk & 1;
;                 const size_t tokk = (size_t)b * SEQL + (rs + i) * 64 + c0 + 8 * (n >> 2) + 4 * hf + (n & 3);
;                 const bf16* kp = KH + ((size_t)h * 2 * MTOK + tokk) * 32 + q4 * 8; const bf16x8 k0 = *(const bf16x8*)kp, k1 = *(const bf16x8*)(kp + (size_t)MTOK * 32);
;                 f32x4 a = (f32x4){0.f, 0.f, 0.f, 0.f};
;                 a = __builtin_amdgcn_mfma_f32_16x16x32_bf16(k0, qf[0], a, 0, 0, 0);
;                 a = __builtin_amdgcn_mfma_f32_16x16x32_bf16(k1, qf[1], a, 0, 0, 0);
;                 acc[blk] = a; }
;             float mx = -3.0e38f;
;             int cofs[8]; bool okk[8];
; #pragma unroll
;             for (int k8 = 0; k8 < 8; ++k8) { const int kc = c0 + 8 * q4 + 4 * (k8 >> 2) + (k8 & 3); okk[k8] = (kc >= cs) && (kc < cs + 16); cofs[k8] = min(max(kc - qcol + 15, 0), 30); }
.LBB0_899:
	s_cmp_lt_i32 s72, 10
	s_cselect_b64 s[4:5], -1, 0
	s_and_b64 s[36:37], s[4:5], s[0:1]
	s_andn2_b64 vcc, exec, s[36:37]
	s_cbranch_vccnz .LBB0_913
	v_lshlrev_b32_e32 v4, 2, v221
	v_add_u32_e32 v3, 0, v4
	s_waitcnt lgkmcnt(0)
	v_add_u32_e32 v6, 0x1000, v4
	v_add_u32_e32 v7, 0x2000, v4
	v_add_u32_e32 v8, 0x3000, v4
	v_add_u32_e32 v9, 0x4000, v4
	v_add_u32_e32 v26, 0x5000, v4
	v_add_u32_e32 v27, 0x6000, v4
	v_add_u32_e32 v28, 0x7000, v4
	global_load_dword v10, v4, s[24:25]
	global_load_dword v11, v4, s[24:25] offset:2048
	global_load_dword v12, v6, s[24:25]
	global_load_dword v13, v6, s[24:25] offset:2048
	global_load_dword v14, v7, s[24:25]
	global_load_dword v15, v7, s[24:25] offset:2048
	global_load_dword v16, v8, s[24:25]
	global_load_dword v17, v8, s[24:25] offset:2048
	global_load_dword v18, v9, s[24:25]
	global_load_dword v19, v9, s[24:25] offset:2048
	global_load_dword v20, v26, s[24:25]
	global_load_dword v21, v26, s[24:25] offset:2048
	global_load_dword v22, v27, s[24:25]
	global_load_dword v23, v27, s[24:25] offset:2048
	v_cmp_gt_u32_e32 vcc, 0x110, v221
	s_nop 1
	s_and_saveexec_b64 s[0:1], vcc
	global_load_dword v24, v28, s[24:25]
	s_mov_b64 exec, s[0:1]
	s_waitcnt vmcnt(0)
	ds_write_b32 v3, v10
	ds_write_b32 v3, v11 offset:2048
	ds_write_b32 v3, v12 offset:4096
	ds_write_b32 v3, v13 offset:6144
	ds_write_b32 v3, v14 offset:8192
	ds_write_b32 v3, v15 offset:10240
	ds_write_b32 v3, v16 offset:12288
	ds_write_b32 v3, v17 offset:14336
	ds_write_b32 v3, v18 offset:16384
	ds_write_b32 v3, v19 offset:18432
	ds_write_b32 v3, v20 offset:20480
	ds_write_b32 v3, v21 offset:22528
	ds_write_b32 v3, v22 offset:24576
	ds_write_b32 v3, v23 offset:26624
	s_and_saveexec_b64 s[0:1], vcc
	ds_write_b32 v3, v24 offset:28672
	s_mov_b64 exec, s[0:1]
	s_ashr_i32 s1, s2, 31
	s_lshr_b32 s1, s1, 29
	s_add_i32 s1, s2, s1
	s_ashr_i32 s3, s1, 3
	s_and_b32 s1, s1, -8
	s_sub_i32 s1, s2, s1
	s_ashr_i32 s4, s74, 3
	s_mul_i32 s1, s4, s1
	s_and_b32 s0, s74, 7
	s_add_i32 s1, s1, s3
	s_cmp_eq_u32 s0, 0
	s_cselect_b32 s3, s1, s2
	s_mov_b32 s47, 0
	s_cmpk_lt_i32 s3, 0x200
	s_waitcnt lgkmcnt(0)
	s_barrier
	s_cbranch_scc0 .LBB0_912
	v_mbcnt_lo_u32_b32 v3, -1, 0
	v_readlane_b32 s0, v248, 14
	v_mbcnt_hi_u32_b32 v3, -1, v3
	s_bfe_u32 s6, s0, 0x20006
	v_and_b32_e32 v5, 64, v3
	s_lshl_b32 s8, s6, 4
	v_xor_b32_e32 v4, 16, v3
	v_add_u32_e32 v5, 64, v5
	s_cmp_eq_u32 s6, 2
	v_cmp_lt_i32_e32 vcc, v4, v5
	v_and_b32_e32 v0, 15, v221
	v_lshrrev_b32_e32 v72, 4, v220
	s_cselect_b32 s7, 24, 32
	v_cndmask_b32_e32 v4, v3, v4, vcc
	s_lshr_b32 s46, s0, 8
	v_or_b32_e32 v1, s8, v0
	v_lshlrev_b32_e32 v48, 3, v72
	v_lshlrev_b32_e32 v73, 2, v4
	v_xor_b32_e32 v4, 32, v3
	s_lshl_b64 s[0:1], s[46:47], 22
	v_sub_u32_e64 v1, v1, 8 clamp
	v_cmp_lt_i32_e32 vcc, v4, v5
	v_lshl_or_b32 v52, v0, 4, s0
	v_mov_b32_e32 v53, s1
	v_add_u32_e32 v75, s8, v0
	v_sub_u32_e32 v0, v48, v0
	s_mul_i32 s1, s46, 0x744
	v_min_u32_e32 v49, 48, v1
	v_mov_b32_e32 v51, 0
	v_lshlrev_b32_e32 v1, 1, v221
	v_and_b32_e32 v2, 3, v221
	v_cndmask_b32_e32 v3, v3, v4, vcc
	v_lshl_or_b32 v50, s46, 7, v48
	s_mov_b64 s[4:5], 0x8000040
	v_subrev_u32_e32 v76, s8, v0
	s_add_i32 s33, s1, 0
	v_add_u32_e32 v57, 16, v49
	v_lshlrev_b32_e32 v74, 2, v3
	v_lshl_add_u64 v[54:55], v[50:51], 0, s[4:5]
	s_addk_i32 s33, 0x364
	v_and_or_b32 v56, v1, 24, v2
	s_cmp_eq_u32 s6, 0
	s_cselect_b32 s98, 2, 3
	s_cmp_eq_u32 s6, 3
	s_cselect_b32 s99, 1, 0
	v_bfe_u32 v252, v221, 2, 2
	v_min_u32_e32 v252, s98, v252
	v_max_u32_e32 v252, s99, v252
	v_and_b32_e32 v253, 3, v221
	v_lshl_or_b32 v56, v252, 3, v253
	v_min_u32_e32 v252, s98, v72
	v_max_u32_e32 v252, s99, v252
	v_and_or_b32 v58, v221, 48, s0
	v_mov_b32_e32 v59, v53
	v_add_u32_e32 v77, 1, v76
	v_add_u32_e32 v78, 2, v76
	v_add_u32_e32 v79, 3, v76
	v_add_u32_e32 v80, 4, v76
	v_add_u32_e32 v81, 5, v76
	v_add_u32_e32 v82, 6, v76
	v_add_u32_e32 v83, 7, v76
	s_movk_i32 s52, 0x7c
	s_brev_b32 s53, 8
	s_mov_b32 s54, 0x10200000
	s_mov_b32 s55, 0x10001000
	s_mov_b32 s56, 0x10201000
	s_mov_b32 s57, 0x10002000
	s_mov_b32 s58, 0x10202000
	s_mov_b32 s59, 0x10003000
	s_mov_b32 s60, 0x10203000
	s_mov_b32 s61, 0x10004000
	s_mov_b32 s62, 0x10204000
	s_mov_b32 s63, 0x10005000
	s_mov_b32 s64, 0x10205000
	s_mov_b32 s65, 0x10006000
	s_mov_b32 s66, 0x10206000
	s_mov_b32 s67, 0x10007000
	s_mov_b32 s76, 0x10207000
	s_mov_b32 s77, 0xff61b1e6
	v_mov_b32_e32 v84, 0xff61b1e6
	s_brev_b32 s78, 40
	s_mov_b32 s79, 0x14002000
	s_mov_b32 s80, 0x14004000
	s_mov_b32 s81, 0x14006000
	s_mov_b32 s82, 0x14008000
	s_mov_b32 s83, 0x1400a000
	s_mov_b32 s84, 0x1400c000
	s_mov_b32 s85, 0x1400e000
	s_mov_b64 s[48:49], 0x800000
	s_mov_b64 s[50:51], 0x100
	s_mov_b32 s86, s3
	s_branch .LBB0_905

; __device__ __forceinline__ void na_phase(const Frame& F, const bf16* QH, const bf16* VB, const float* rpb, bf16* U) {
;     ...
;             const int hj = it * 8 + F.wave, h = hj >> 2, j = hj & 3;
;             const int c0 = (j == 0) ? 0 : (j == 1) ? 8 : (j == 2) ? 24 : 32;
;             const int qcol = 16 * j + n, cs = min(max(qcol - 8, 0), 48);
;             const size_t tokq = (size_t)b * SEQL + r * 64 + qcol;
;             bf16x8 qf[2];
; #pragma unroll
;             for (int ks = 0; ks < 2; ++ks) qf[ks] = *(const bf16x8*)(QH + (((size_t)h * 2 + ks) * MTOK + tokq) * 32 + q4 * 8);
;             f32x4 acc[16];
; #pragma unroll
;             for (int blk = 0; blk < 16; ++blk) { const int i = blk >> 1, hf = blk & 1;
;                 const size_t tokk = (size_t)b * SEQL + (rs + i) * 64 + c0 + 8 * (n >> 2) + 4 * hf + (n & 3);
;                 const bf16* kp = KH + ((size_t)h * 2 * MTOK + tokk) * 32 + q4 * 8; const bf16x8 k0 = *(const bf16x8*)kp, k1 = *(const bf16x8*)(kp + (size_t)MTOK * 32);
;                 f32x4 a = (f32x4){0.f, 0.f, 0.f, 0.f};
;                 a = __builtin_amdgcn_mfma_f32_16x16x32_bf16(k0, qf[0], a, 0, 0, 0);
;                 a = __builtin_amdgcn_mfma_f32_16x16x32_bf16(k1, qf[1], a, 0, 0, 0);
;                 acc[blk] = a; }
.LBB0_906:
	v_lshl_add_u64 v[0:1], s[70:71], 0, v[68:69]
	v_add_co_u32_e32 v2, vcc, 0xc000000, v0
	v_add_lshl_u32 v50, v56, s46, 6
	s_nop 0
	v_addc_co_u32_e32 v3, vcc, 0, v1, vcc
	v_add_co_u32_e32 v4, vcc, 0xc200000, v0
	v_lshl_add_u64 v[68:69], v[68:69], 0, s[48:49]
	s_nop 0
	v_addc_co_u32_e32 v5, vcc, 0, v1, vcc
	global_load_dwordx4 v[0:3], v[2:3], off
	s_nop 0
	global_load_dwordx4 v[86:89], v[4:5], off
	v_lshl_add_u64 v[4:5], v[64:65], 0, s[46:47]
	v_lshlrev_b64 v[4:5], 6, v[4:5]
	v_lshl_add_u64 v[4:5], v[70:71], 0, v[4:5]
	v_lshl_add_u64 v[4:5], s[70:71], 0, v[4:5]
	v_add_co_u32_e32 v8, vcc, 0x10000000, v4
	v_lshl_add_u64 v[70:71], v[70:71], 0, s[48:49]
	s_nop 0
	v_addc_co_u32_e32 v9, vcc, 0, v5, vcc
	v_add_co_u32_e32 v12, vcc, 0x10200000, v4
	s_nop 1
	v_addc_co_u32_e32 v13, vcc, 0, v5, vcc
	v_lshl_add_u64 v[4:5], v[66:67], 0, v[50:51]
	v_lshl_add_u64 v[114:115], s[70:71], 0, v[4:5]
	v_add_co_u32_e32 v106, vcc, s61, v114
	v_add_u32_e32 v50, s46, v48
	s_nop 0
	v_addc_co_u32_e32 v107, vcc, 0, v115, vcc
	v_add_co_u32_e32 v16, vcc, s53, v114
	global_load_dwordx4 v[4:7], v[106:107], off offset:-4096
	s_nop 0
	global_load_dwordx4 v[8:11], v[8:9], off
	s_nop 0
	global_load_dwordx4 v[12:15], v[12:13], off
	v_addc_co_u32_e32 v17, vcc, 0, v115, vcc
	v_add_co_u32_e32 v28, vcc, s54, v114
	s_mov_b64 s[0:1], vcc
	v_add_co_u32_e32 v20, vcc, s55, v114
	global_load_dwordx4 v[16:19], v[16:17], off offset:256
	s_nop 0
	v_addc_co_u32_e32 v21, vcc, 0, v115, vcc
	global_load_dwordx4 v[20:23], v[20:21], off offset:256
	s_nop 0
	global_load_dwordx4 v[24:27], v[106:107], off
	v_addc_co_u32_e64 v29, vcc, 0, v115, s[0:1]
	v_add_co_u32_e32 v36, vcc, s57, v114
	global_load_dwordx4 v[28:31], v[28:29], off offset:256
	s_nop 0
	v_addc_co_u32_e32 v37, vcc, 0, v115, vcc
	v_add_co_u32_e32 v38, vcc, s56, v114
	global_load_dwordx4 v[32:35], v[36:37], off offset:-4096
	s_nop 0
	v_addc_co_u32_e32 v39, vcc, 0, v115, vcc
	v_add_co_u32_e32 v40, vcc, s58, v114
	v_cmp_lt_u32_e64 s[0:1], v50, v57
	s_nop 0
	v_addc_co_u32_e32 v41, vcc, 0, v115, vcc
	v_add_co_u32_e32 v108, vcc, s62, v114
	v_lshl_add_u64 v[66:67], v[66:67], 0, s[48:49]
	s_nop 0
	v_addc_co_u32_e32 v109, vcc, 0, v115, vcc
	s_waitcnt vmcnt(7)
	v_mfma_f32_16x16x32_bf16 v[4:7], v[4:7], v[0:3], 0
	s_waitcnt vmcnt(6)
	v_mfma_f32_16x16x32_bf16 v[8:11], v[8:11], v[0:3], 0
	s_waitcnt vmcnt(5)
	v_mfma_f32_16x16x32_bf16 v[90:93], v[12:15], v[86:89], v[8:11]
	s_waitcnt vmcnt(3)
	v_mfma_f32_16x16x32_bf16 v[12:15], v[20:23], v[0:3], 0
	s_nop 3
	global_load_dwordx4 v[8:11], v[38:39], off offset:256
	global_load_dwordx4 v[20:23], v[36:37], off
	s_nop 0
	global_load_dwordx4 v[36:39], v[36:37], off offset:256
	v_mfma_f32_16x16x32_bf16 v[16:19], v[16:19], v[0:3], 0
	s_waitcnt vmcnt(4)
	v_mfma_f32_16x16x32_bf16 v[94:97], v[28:31], v[86:89], v[16:19]
	s_nop 5
	global_load_dwordx4 v[16:19], v[40:41], off offset:-4096
	s_waitcnt vmcnt(4)
	v_mfma_f32_16x16x32_bf16 v[32:35], v[32:35], v[0:3], 0
	s_waitcnt vmcnt(3)
	v_mfma_f32_16x16x32_bf16 v[98:101], v[8:11], v[86:89], v[12:15]
	s_nop 2
	v_add_co_u32_e32 v12, vcc, s59, v114
	s_waitcnt vmcnt(1)
	v_mfma_f32_16x16x32_bf16 v[28:31], v[36:39], v[0:3], 0
	global_load_dwordx4 v[36:39], v[40:41], off
	s_nop 0
	global_load_dwordx4 v[40:43], v[40:41], off offset:256
	v_addc_co_u32_e32 v13, vcc, 0, v115, vcc
	global_load_dwordx4 v[8:11], v[108:109], off offset:-4096
	v_mfma_f32_16x16x32_bf16 v[20:23], v[20:23], v[0:3], 0
	global_load_dwordx4 v[12:15], v[12:13], off offset:256
	s_waitcnt vmcnt(4)
	v_mfma_f32_16x16x32_bf16 v[102:105], v[16:19], v[86:89], v[32:35]
	global_load_dwordx4 v[16:19], v[106:107], off offset:256
	s_waitcnt vmcnt(4)
	v_mfma_f32_16x16x32_bf16 v[44:47], v[36:39], v[86:89], v[20:23]
	s_nop 2
	v_add_co_u32_e32 v20, vcc, s60, v114
	s_nop 1
	v_addc_co_u32_e32 v21, vcc, 0, v115, vcc
	s_waitcnt vmcnt(2)
	v_mfma_f32_16x16x32_bf16 v[36:39], v[8:11], v[86:89], v[4:7]
	s_nop 2
	global_load_dwordx4 v[4:7], v[20:21], off offset:256
	s_waitcnt vmcnt(2)
	v_mfma_f32_16x16x32_bf16 v[8:11], v[12:15], v[0:3], 0
	v_mfma_f32_16x16x32_bf16 v[40:43], v[40:43], v[86:89], v[28:31]
	s_nop 2
	v_add_co_u32_e32 v28, vcc, s65, v114
	s_waitcnt vmcnt(0)
	v_mfma_f32_16x16x32_bf16 v[32:35], v[4:7], v[86:89], v[8:11]
	s_nop 2
	global_load_dwordx4 v[8:11], v[108:109], off
	global_load_dwordx4 v[12:15], v[108:109], off offset:256
	v_addc_co_u32_e32 v29, vcc, 0, v115, vcc
	v_mfma_f32_16x16x32_bf16 v[4:7], v[24:27], v[0:3], 0
	v_add_co_u32_e32 v110, vcc, s66, v114
	global_load_dwordx4 v[106:109], v[28:29], off offset:256
	s_waitcnt vmcnt(2)
	v_mfma_f32_16x16x32_bf16 v[20:23], v[8:11], v[86:89], v[4:7]
	s_nop 3
	global_load_dwordx4 v[4:7], v[28:29], off offset:-4096
	v_addc_co_u32_e32 v111, vcc, 0, v115, vcc
	v_mfma_f32_16x16x32_bf16 v[8:11], v[16:19], v[0:3], 0
	global_load_dwordx4 v[16:19], v[110:111], off offset:-4096
	s_waitcnt vmcnt(3)
	v_mfma_f32_16x16x32_bf16 v[24:27], v[12:15], v[86:89], v[8:11]
	v_add_co_u32_e32 v12, vcc, s63, v114
	s_nop 1
	v_addc_co_u32_e32 v13, vcc, 0, v115, vcc
	global_load_dwordx4 v[12:15], v[12:13], off offset:256
	v_add_co_u32_e32 v112, vcc, s64, v114
	global_load_dwordx4 v[8:11], v[28:29], off
	s_nop 0
	v_addc_co_u32_e32 v113, vcc, 0, v115, vcc
	v_add_co_u32_e32 v116, vcc, s67, v114
	s_waitcnt vmcnt(3)
	v_mfma_f32_16x16x32_bf16 v[4:7], v[4:7], v[0:3], 0
	v_addc_co_u32_e32 v117, vcc, 0, v115, vcc
	v_add_co_u32_e32 v114, vcc, s76, v114
	s_waitcnt vmcnt(2)
	v_mfma_f32_16x16x32_bf16 v[28:31], v[16:19], v[86:89], v[4:7]
	v_addc_co_u32_e32 v115, vcc, 0, v115, vcc
	v_cmp_ge_u32_e32 vcc, v50, v49
	s_nop 1
	global_load_dwordx4 v[4:7], v[112:113], off offset:256
	s_waitcnt vmcnt(2)
; #define LAS __attribute__((address_space(3)))
; __device__ __forceinline__ void na_phase(const Frame& F, const bf16* QH, const bf16* VB, const float* rpb, bf16* U) {
;     ...
;             for (int blk = 0; blk < 16; ++blk) { const int i = blk >> 1, hf = blk & 1;
;                 const size_t tokk = (size_t)b * SEQL + (rs + i) * 64 + c0 + 8 * (n >> 2) + 4 * hf + (n & 3);
;                 const bf16* kp = KH + ((size_t)h * 2 * MTOK + tokk) * 32 + q4 * 8; const bf16x8 k0 = *(const bf16x8*)kp, k1 = *(const bf16x8*)(kp + (size_t)MTOK * 32);
;                 f32x4 a = (f32x4){0.f, 0.f, 0.f, 0.f};
;                 a = __builtin_amdgcn_mfma_f32_16x16x32_bf16(k0, qf[0], a, 0, 0, 0);
;                 a = __builtin_amdgcn_mfma_f32_16x16x32_bf16(k1, qf[1], a, 0, 0, 0);
;                 acc[blk] = a; }
;             float mx = -3.0e38f;
;             int cofs[8]; bool okk[8];
; #pragma unroll
;             for (int k8 = 0; k8 < 8; ++k8) { const int kc = c0 + 8 * q4 + 4 * (k8 >> 2) + (k8 & 3); okk[k8] = (kc >= cs) && (kc < cs + 16); cofs[k8] = min(max(kc - qcol + 15, 0), 30); }
; #pragma unroll
;             for (int i = 0; i < 8; ++i) { const LAS float* rprow = RP + (h * 15 + (rs + i - r + 7)) * 31;
; #pragma unroll
;                 for (int k8 = 0; k8 < 8; ++k8) { const int blk = 2 * i + (k8 >> 2), e = k8 & 3;
;                     const float bia = rprow[cofs[k8]];
;                     const float sb = acc[blk][e] * 0.125f + bia; const float s = okk[k8] ? sb : -3.0e38f;
;                     acc[blk][e] = s; mx = fmaxf(mx, s); } }
	v_mfma_f32_16x16x32_bf16 v[12:15], v[12:15], v[0:3], 0
	s_and_b64 vcc, vcc, s[0:1]
	s_waitcnt vmcnt(0)
	v_mfma_f32_16x16x32_bf16 v[16:19], v[4:7], v[86:89], v[12:15]
	v_mfma_f32_16x16x32_bf16 v[4:7], v[8:11], v[0:3], 0
	global_load_dwordx4 v[8:11], v[110:111], off
	s_nop 0
	global_load_dwordx4 v[110:113], v[110:111], off offset:256
	s_waitcnt vmcnt(1)
	v_mfma_f32_16x16x32_bf16 v[12:15], v[8:11], v[86:89], v[4:7]
	s_nop 2
	global_load_dwordx4 v[4:7], v[116:117], off
	v_mfma_f32_16x16x32_bf16 v[8:11], v[106:109], v[0:3], 0
	global_load_dwordx4 v[106:109], v[114:115], off
	s_waitcnt vmcnt(2)
	v_mfma_f32_16x16x32_bf16 v[8:11], v[110:113], v[86:89], v[8:11]
	global_load_dwordx4 v[110:113], v[116:117], off offset:256
	s_nop 0
	global_load_dwordx4 v[114:117], v[114:115], off offset:256
	s_waitcnt vmcnt(3)
	v_mfma_f32_16x16x32_bf16 v[4:7], v[4:7], v[0:3], 0
	s_waitcnt vmcnt(1)
	v_mfma_f32_16x16x32_bf16 v[0:3], v[110:113], v[0:3], 0
	v_add_u32_e32 v110, s87, v85
	s_addk_i32 s87, 0xe88
	v_mfma_f32_16x16x32_bf16 v[4:7], v[106:109], v[86:89], v[4:7]
	s_waitcnt vmcnt(0)
	v_mfma_f32_16x16x32_bf16 v[0:3], v[114:117], v[86:89], v[0:3]
	v_or_b32_e32 v86, 1, v50
	v_cmp_ge_u32_e64 s[4:5], v86, v49
	v_cmp_lt_u32_e64 s[8:9], v86, v57
	v_or_b32_e32 v86, 2, v50
	v_cmp_ge_u32_e64 s[10:11], v86, v49
	v_cmp_lt_u32_e64 s[12:13], v86, v57
	v_or_b32_e32 v86, 3, v50
	v_cmp_ge_u32_e64 s[14:15], v86, v49
	v_cmp_lt_u32_e64 s[16:17], v86, v57
	v_or_b32_e32 v86, 4, v50
	v_cmp_ge_u32_e64 s[18:19], v86, v49
	v_cmp_lt_u32_e64 s[20:21], v86, v57
	v_or_b32_e32 v86, 5, v50
	v_cmp_ge_u32_e64 s[22:23], v86, v49
	v_cmp_lt_u32_e64 s[24:25], v86, v57
	v_or_b32_e32 v86, 6, v50
	v_cmp_ge_u32_e64 s[26:27], v86, v49
	v_cmp_lt_u32_e64 s[28:29], v86, v57
	v_add_u32_e32 v86, s46, v76
	v_add_u32_e32 v88, s46, v77
	v_max_i32_e32 v86, -15, v86
	v_max_i32_e32 v88, -15, v88
	v_add_u32_e32 v86, 15, v86
	v_add_u32_e32 v88, 15, v88
	v_min_u32_e32 v86, 30, v86
	v_min_u32_e32 v88, 30, v88
	v_lshl_add_u32 v112, v86, 2, v110
	v_lshl_add_u32 v113, v88, 2, v110
	ds_read2_b32 v[86:87], v112 offset1:31
	ds_read2_b32 v[88:89], v113 offset1:31
	v_or_b32_e32 v50, 7, v50
	v_cmp_ge_u32_e64 s[30:31], v50, v49
	v_cmp_lt_u32_e64 s[34:35], v50, v57
	s_waitcnt lgkmcnt(1)
	v_fmamk_f32 v50, v90, 0x3e000000, v86
	s_waitcnt lgkmcnt(0)
	v_fmamk_f32 v86, v91, 0x3e000000, v88
	s_and_b64 s[0:1], s[4:5], s[8:9]
	v_cndmask_b32_e64 v114, v84, v86, s[0:1]
	v_add_u32_e32 v86, s46, v78
	v_max_i32_e32 v86, -15, v86
	v_add_u32_e32 v86, 15, v86
	v_min_u32_e32 v86, 30, v86
	v_lshl_add_u32 v115, v86, 2, v110
	v_add_u32_e32 v86, s46, v79
	v_max_i32_e32 v86, -15, v86
	v_add_u32_e32 v86, 15, v86
	v_min_u32_e32 v86, 30, v86
	ds_read2_b32 v[90:91], v115 offset1:31
	v_lshl_add_u32 v116, v86, 2, v110
	ds_read2_b32 v[106:107], v116 offset1:31
	s_and_b64 s[4:5], s[10:11], s[12:13]
	s_and_b64 s[8:9], s[14:15], s[16:17]
	s_waitcnt lgkmcnt(1)
	v_fmamk_f32 v88, v92, 0x3e000000, v90
	v_cndmask_b32_e64 v117, v84, v88, s[4:5]
	s_waitcnt lgkmcnt(0)
	v_fmamk_f32 v88, v93, 0x3e000000, v106
	v_cndmask_b32_e64 v106, v84, v88, s[8:9]
	v_add_u32_e32 v88, s46, v80
	v_max_i32_e32 v88, -15, v88
	v_add_u32_e32 v88, 15, v88
	v_min_u32_e32 v88, 30, v88
	v_lshl_add_u32 v118, v88, 2, v110
	v_add_u32_e32 v88, s46, v81
	v_max_i32_e32 v88, -15, v88
	v_add_u32_e32 v88, 15, v88
	v_min_u32_e32 v88, 30, v88
	ds_read2_b32 v[92:93], v118 offset1:31
	v_lshl_add_u32 v119, v88, 2, v110
	ds_read2_b32 v[108:109], v119 offset1:31
	s_and_b64 s[10:11], s[18:19], s[20:21]
	s_and_b64 s[12:13], s[22:23], s[24:25]
	s_waitcnt lgkmcnt(1)
	v_fmamk_f32 v88, v94, 0x3e000000, v92
	v_cndmask_b32_e64 v120, v84, v88, s[10:11]
	s_waitcnt lgkmcnt(0)
	v_fmamk_f32 v88, v95, 0x3e000000, v108
	v_cndmask_b32_e64 v108, v84, v88, s[12:13]
	v_add_u32_e32 v88, s46, v82
	v_max_i32_e32 v88, -15, v88
	v_add_u32_e32 v88, 15, v88
	v_min_u32_e32 v88, 30, v88
	v_lshl_add_u32 v121, v88, 2, v110
	v_add_u32_e32 v88, s46, v83
	v_max_i32_e32 v88, -15, v88
	v_add_u32_e32 v88, 15, v88
	v_min_u32_e32 v88, 30, v88
	ds_read2_b32 v[94:95], v121 offset1:31
	v_lshl_add_u32 v122, v88, 2, v110
	ds_read2_b32 v[110:111], v122 offset1:31
	v_cndmask_b32_e32 v50, v84, v50, vcc
	v_max3_f32 v86, v50, s77, v114
	s_waitcnt lgkmcnt(1)
	v_fmamk_f32 v88, v96, 0x3e000000, v94
	s_and_b64 s[14:15], s[26:27], s[28:29]
	v_max3_f32 v86, v86, v117, v106
	v_cndmask_b32_e64 v96, v84, v88, s[14:15]
	s_waitcnt lgkmcnt(0)
	v_fmamk_f32 v88, v97, 0x3e000000, v110
	s_and_b64 s[16:17], s[30:31], s[34:35]
	v_max3_f32 v86, v86, v120, v108
	v_cndmask_b32_e64 v97, v84, v88, s[16:17]
	v_fmac_f32_e32 v87, 0x3e000000, v102
	v_fmac_f32_e32 v89, 0x3e000000, v103
	v_max3_f32 v86, v86, v96, v97
	v_cndmask_b32_e32 v102, v84, v87, vcc
	v_cndmask_b32_e64 v103, v84, v89, s[0:1]
	v_fmac_f32_e32 v91, 0x3e000000, v104
	v_fmac_f32_e32 v107, 0x3e000000, v105
	v_max3_f32 v86, v86, v102, v103
	v_cndmask_b32_e64 v104, v84, v91, s[4:5]
	v_cndmask_b32_e64 v105, v84, v107, s[8:9]
	v_fmac_f32_e32 v93, 0x3e000000, v98
	v_fmac_f32_e32 v109, 0x3e000000, v99
	v_max3_f32 v86, v86, v104, v105
	v_cndmask_b32_e64 v98, v84, v93, s[10:11]
	v_cndmask_b32_e64 v99, v84, v109, s[12:13]
	v_max3_f32 v90, v86, v98, v99
	ds_read2_b32 v[86:87], v112 offset0:62 offset1:93
	ds_read2_b32 v[88:89], v113 offset0:62 offset1:93
	v_fmac_f32_e32 v95, 0x3e000000, v100
	v_fmac_f32_e32 v111, 0x3e000000, v101
	v_cndmask_b32_e64 v100, v84, v95, s[14:15]
	v_cndmask_b32_e64 v101, v84, v111, s[16:17]
	s_waitcnt lgkmcnt(1)
	v_fmamk_f32 v44, v44, 0x3e000000, v86
	v_max3_f32 v92, v90, v100, v101
	v_cndmask_b32_e32 v86, v84, v44, vcc
	ds_read2_b32 v[90:91], v115 offset0:62 offset1:93
	s_waitcnt lgkmcnt(1)
; #define LAS __attribute__((address_space(3)))
; __device__ __forceinline__ void na_phase(const Frame& F, const bf16* QH, const bf16* VB, const float* rpb, bf16* U) {
;     ...
;             for (int i = 0; i < 8; ++i) { const LAS float* rprow = RP + (h * 15 + (rs + i - r + 7)) * 31;
; #pragma unroll
;                 for (int k8 = 0; k8 < 8; ++k8) { const int blk = 2 * i + (k8 >> 2), e = k8 & 3;
;                     const float bia = rprow[cofs[k8]];
;                     const float sb = acc[blk][e] * 0.125f + bia; const float s = okk[k8] ? sb : -3.0e38f;
;                     acc[blk][e] = s; mx = fmaxf(mx, s); } }
	v_fmamk_f32 v44, v45, 0x3e000000, v88
	v_cndmask_b32_e64 v88, v84, v44, s[0:1]
	ds_read2_b32 v[44:45], v116 offset0:62 offset1:93
	v_max3_f32 v94, v92, v86, v88
	s_waitcnt lgkmcnt(1)
	v_fmamk_f32 v46, v46, 0x3e000000, v90
	ds_read2_b32 v[92:93], v118 offset0:62 offset1:93
	v_cndmask_b32_e64 v90, v84, v46, s[4:5]
	s_waitcnt lgkmcnt(1)
	v_fmamk_f32 v44, v47, 0x3e000000, v44
	ds_read2_b32 v[46:47], v119 offset0:62 offset1:93
	v_cndmask_b32_e64 v44, v84, v44, s[8:9]
	s_waitcnt lgkmcnt(1)
	v_fmamk_f32 v40, v40, 0x3e000000, v92
	v_max3_f32 v107, v94, v90, v44
	v_cndmask_b32_e64 v92, v84, v40, s[10:11]
	ds_read2_b32 v[94:95], v121 offset0:62 offset1:93
	s_waitcnt lgkmcnt(1)
	v_fmamk_f32 v46, v41, 0x3e000000, v46
	ds_read2_b32 v[40:41], v122 offset0:62 offset1:93
	v_cndmask_b32_e64 v46, v84, v46, s[12:13]
	v_fmac_f32_e32 v93, 0x3e000000, v32
	s_waitcnt lgkmcnt(1)
	v_fmamk_f32 v42, v42, 0x3e000000, v94
	v_fmac_f32_e32 v47, 0x3e000000, v33
	s_waitcnt lgkmcnt(0)
	v_fmamk_f32 v40, v43, 0x3e000000, v40
	ds_read2_b32 v[32:33], v112 offset0:124 offset1:155
	v_max3_f32 v107, v107, v92, v46
	v_cndmask_b32_e64 v42, v84, v42, s[14:15]
	v_cndmask_b32_e64 v43, v84, v40, s[16:17]
	v_fmac_f32_e32 v87, 0x3e000000, v36
	v_fmac_f32_e32 v89, 0x3e000000, v37
	v_fmac_f32_e32 v95, 0x3e000000, v34
	v_fmac_f32_e32 v41, 0x3e000000, v35
	ds_read2_b32 v[34:35], v113 offset0:124 offset1:155
	v_max3_f32 v40, v107, v42, v43
	v_cndmask_b32_e32 v87, v84, v87, vcc
	v_cndmask_b32_e64 v89, v84, v89, s[0:1]
	v_fmac_f32_e32 v91, 0x3e000000, v38
	v_fmac_f32_e32 v45, 0x3e000000, v39
	v_max3_f32 v36, v40, v87, v89
	v_cndmask_b32_e64 v91, v84, v91, s[4:5]
	v_cndmask_b32_e64 v45, v84, v45, s[8:9]
	v_max3_f32 v36, v36, v91, v45
	v_cndmask_b32_e64 v93, v84, v93, s[10:11]
	v_cndmask_b32_e64 v47, v84, v47, s[12:13]
	v_max3_f32 v36, v36, v93, v47
	v_cndmask_b32_e64 v94, v84, v95, s[14:15]
	v_cndmask_b32_e64 v95, v84, v41, s[16:17]
	s_waitcnt lgkmcnt(1)
	v_fmamk_f32 v20, v20, 0x3e000000, v32
	v_max3_f32 v38, v36, v94, v95
	v_cndmask_b32_e32 v107, v84, v20, vcc
	ds_read2_b32 v[36:37], v115 offset0:124 offset1:155
	s_waitcnt lgkmcnt(1)
	v_fmamk_f32 v20, v21, 0x3e000000, v34
	v_cndmask_b32_e64 v34, v84, v20, s[0:1]
	ds_read2_b32 v[20:21], v116 offset0:124 offset1:155
	v_max3_f32 v32, v38, v107, v34
	s_waitcnt lgkmcnt(1)
	v_fmamk_f32 v22, v22, 0x3e000000, v36
	ds_read2_b32 v[38:39], v118 offset0:124 offset1:155
	v_cndmask_b32_e64 v36, v84, v22, s[4:5]
	s_waitcnt lgkmcnt(1)
	v_fmamk_f32 v20, v23, 0x3e000000, v20
	ds_read2_b32 v[22:23], v119 offset0:124 offset1:155
	ds_read2_b32 v[40:41], v121 offset0:124 offset1:155
	s_waitcnt lgkmcnt(2)
	v_fmamk_f32 v24, v24, 0x3e000000, v38
	v_cndmask_b32_e64 v38, v84, v24, s[10:11]
	v_cndmask_b32_e64 v109, v84, v20, s[8:9]
	s_waitcnt lgkmcnt(1)
	v_fmamk_f32 v22, v25, 0x3e000000, v22
	ds_read2_b32 v[24:25], v122 offset0:124 offset1:155
	v_cndmask_b32_e64 v110, v84, v22, s[12:13]
	s_waitcnt lgkmcnt(1)
	v_fmamk_f32 v22, v26, 0x3e000000, v40
	v_max3_f32 v20, v32, v36, v109
	v_cndmask_b32_e64 v40, v84, v22, s[14:15]
	s_waitcnt lgkmcnt(0)
	v_fmamk_f32 v22, v27, 0x3e000000, v24
	v_max3_f32 v20, v20, v38, v110
	v_cndmask_b32_e64 v111, v84, v22, s[16:17]
	v_fmac_f32_e32 v33, 0x3e000000, v28
	v_fmac_f32_e32 v35, 0x3e000000, v29
	v_max3_f32 v20, v20, v40, v111
	v_cndmask_b32_e32 v123, v84, v33, vcc
	v_cndmask_b32_e64 v35, v84, v35, s[0:1]
	v_fmac_f32_e32 v37, 0x3e000000, v30
	v_fmac_f32_e32 v21, 0x3e000000, v31
	v_max3_f32 v20, v20, v123, v35
	v_cndmask_b32_e64 v37, v84, v37, s[4:5]
	v_cndmask_b32_e64 v124, v84, v21, s[8:9]
	v_fmac_f32_e32 v39, 0x3e000000, v16
	v_fmac_f32_e32 v23, 0x3e000000, v17
	v_max3_f32 v20, v20, v37, v124
	v_cndmask_b32_e64 v125, v84, v39, s[10:11]
	v_cndmask_b32_e64 v126, v84, v23, s[12:13]
	v_max3_f32 v16, v20, v125, v126
	ds_read2_b32 v[20:21], v112 offset0:186 offset1:217
	v_fmac_f32_e32 v41, 0x3e000000, v18
	v_fmac_f32_e32 v25, 0x3e000000, v19
	ds_read2_b32 v[18:19], v113 offset0:186 offset1:217
	v_cndmask_b32_e64 v127, v84, v41, s[14:15]
	v_cndmask_b32_e64 v112, v84, v25, s[16:17]
	s_waitcnt lgkmcnt(1)
	v_fmamk_f32 v12, v12, 0x3e000000, v20
	v_max3_f32 v26, v16, v127, v112
	v_cndmask_b32_e32 v16, v84, v12, vcc
	s_waitcnt lgkmcnt(0)
	v_fmamk_f32 v12, v13, 0x3e000000, v18
	ds_read2_b32 v[22:23], v115 offset0:186 offset1:217
	v_cndmask_b32_e64 v17, v84, v12, s[0:1]
	ds_read2_b32 v[24:25], v116 offset0:186 offset1:217
	v_max3_f32 v12, v26, v16, v17
	ds_read2_b32 v[26:27], v118 offset0:186 offset1:217
	ds_read2_b32 v[28:29], v119 offset0:186 offset1:217
	ds_read2_b32 v[30:31], v121 offset0:186 offset1:217
	ds_read2_b32 v[32:33], v122 offset0:186 offset1:217
	s_waitcnt lgkmcnt(5)
	v_fmamk_f32 v13, v14, 0x3e000000, v22
	v_cndmask_b32_e64 v18, v84, v13, s[4:5]
	s_waitcnt lgkmcnt(4)
	v_fmamk_f32 v13, v15, 0x3e000000, v24
	s_waitcnt lgkmcnt(3)
	v_fmamk_f32 v8, v8, 0x3e000000, v26
	v_cndmask_b32_e64 v15, v84, v13, s[8:9]
	v_cndmask_b32_e64 v14, v84, v8, s[10:11]
	s_waitcnt lgkmcnt(2)
	v_fmamk_f32 v8, v9, 0x3e000000, v28
	v_max3_f32 v12, v12, v18, v15
	v_cndmask_b32_e64 v13, v84, v8, s[12:13]
	s_waitcnt lgkmcnt(1)
	v_fmamk_f32 v9, v10, 0x3e000000, v30
	v_max3_f32 v8, v12, v14, v13
	v_cndmask_b32_e64 v12, v84, v9, s[14:15]
	s_waitcnt lgkmcnt(0)
; __device__ __forceinline__ unsigned pk2(float lo, float hi) { unsigned r; asm("v_cvt_pk_bf16_f32 %0, %1, %2" : "=v"(r) : "v"(lo), "v"(hi)); return r; }
; __device__ __forceinline__ void na_phase(const Frame& F, const bf16* QH, const bf16* VB, const float* rpb, bf16* U) {
;     ...
;             mx = fmaxf(mx, __shfl_xor(mx, 16)); mx = fmaxf(mx, __shfl_xor(mx, 32));
;             float sum = 0.f;
; #pragma unroll
;             for (int blk = 0; blk < 16; ++blk)
; #pragma unroll
;                 for (int e = 0; e < 4; ++e) { const float p = __builtin_amdgcn_exp2f((acc[blk][e] - mx) * 1.44269504089f); acc[blk][e] = p; sum += p; }
;             sum += __shfl_xor(sum, 16); sum += __shfl_xor(sum, 32);
;             const float inv = 1.0f / sum;
;             f32x4 o[4];
; #pragma unroll
;             for (int db = 0; db < 4; ++db) o[db] = (f32x4){0.f, 0.f, 0.f, 0.f};
; #pragma unroll
;             for (int i = 0; i < 8; ++i) {
;                 v4u pw; pw.x = pk2(acc[2 * i][0], acc[2 * i][1]); pw.y = pk2(acc[2 * i][2], acc[2 * i][3]); pw.z = pk2(acc[2 * i + 1][0], acc[2 * i + 1][1]); pw.w = pk2(acc[2 * i + 1][2], acc[2 * i + 1][3]);
;                 const bf16x8 pf = __builtin_bit_cast(bf16x8, pw);
;                 const size_t vrow = (((size_t)h * 512 + b * 256 + rs + i) * 8 + (c0 >> 3) + q4) * 512;
; #pragma unroll
;                 for (int db = 0; db < 4; ++db) { const bf16x8 vfrag = *(const bf16x8*)(VB + vrow + (16 * db + n) * 8);
	v_fmamk_f32 v9, v11, 0x3e000000, v32
	v_cndmask_b32_e64 v11, v84, v9, s[16:17]
	v_fmac_f32_e32 v21, 0x3e000000, v4
	v_fmac_f32_e32 v19, 0x3e000000, v5
	v_max3_f32 v8, v8, v12, v11
	v_cndmask_b32_e32 v10, v84, v21, vcc
	v_cndmask_b32_e64 v9, v84, v19, s[0:1]
	v_fmac_f32_e32 v23, 0x3e000000, v6
	v_fmac_f32_e32 v25, 0x3e000000, v7
	v_max3_f32 v4, v8, v10, v9
	v_cndmask_b32_e64 v8, v84, v23, s[4:5]
	v_cndmask_b32_e64 v6, v84, v25, s[8:9]
	v_fmac_f32_e32 v27, 0x3e000000, v0
	v_fmac_f32_e32 v29, 0x3e000000, v1
	v_max3_f32 v7, v4, v8, v6
	v_cndmask_b32_e64 v5, v84, v27, s[10:11]
	v_cndmask_b32_e64 v4, v84, v29, s[12:13]
	v_fmac_f32_e32 v31, 0x3e000000, v2
	v_fmac_f32_e32 v33, 0x3e000000, v3
	v_max3_f32 v7, v7, v5, v4
	v_cndmask_b32_e64 v1, v84, v31, s[14:15]
	v_cndmask_b32_e64 v0, v84, v33, s[16:17]
	v_max3_f32 v2, v7, v1, v0
	ds_bpermute_b32 v3, v73, v2
	s_lshr_b32 s0, s46, 3
	s_cmpk_eq_i32 s87, 0x7440
	s_waitcnt lgkmcnt(0)
	v_max_f32_e32 v3, v3, v3
	v_max_f32_e32 v2, v2, v3
	ds_bpermute_b32 v3, v74, v2
	s_waitcnt lgkmcnt(0)
	v_max_f32_e32 v3, v3, v3
	v_max_f32_e32 v2, v2, v3
	v_sub_f32_e32 v20, v117, v2
	v_mul_f32_e32 v20, 0x3fb8aa3b, v20
	v_exp_f32_e32 v115, v20
	v_sub_f32_e32 v20, v106, v2
	v_mul_f32_e32 v20, 0x3fb8aa3b, v20
	v_exp_f32_e32 v118, v20
	v_sub_f32_e32 v20, v120, v2
	v_mul_f32_e32 v20, 0x3fb8aa3b, v20
	v_exp_f32_e32 v128, v20
	v_sub_f32_e32 v20, v108, v2
	v_mul_f32_e32 v20, 0x3fb8aa3b, v20
	v_exp_f32_e32 v129, v20
	v_sub_f32_e32 v20, v96, v2
	v_mul_f32_e32 v20, 0x3fb8aa3b, v20
	v_exp_f32_e32 v130, v20
	v_sub_f32_e32 v20, v97, v2
	v_mul_f32_e32 v20, 0x3fb8aa3b, v20
	v_exp_f32_e32 v131, v20
	v_sub_f32_e32 v20, v102, v2
	v_mul_f32_e32 v20, 0x3fb8aa3b, v20
	v_exp_f32_e32 v142, v20
	v_sub_f32_e32 v20, v103, v2
	v_mul_f32_e32 v20, 0x3fb8aa3b, v20
	v_exp_f32_e32 v143, v20
	v_sub_f32_e32 v20, v104, v2
	v_mul_f32_e32 v20, 0x3fb8aa3b, v20
	v_exp_f32_e32 v144, v20
	v_sub_f32_e32 v20, v105, v2
	v_mul_f32_e32 v20, 0x3fb8aa3b, v20
	v_exp_f32_e32 v145, v20
	v_sub_f32_e32 v20, v98, v2
	v_mul_f32_e32 v20, 0x3fb8aa3b, v20
	v_exp_f32_e32 v146, v20
	v_sub_f32_e32 v20, v99, v2
	v_mul_f32_e32 v20, 0x3fb8aa3b, v20
	v_exp_f32_e32 v147, v20
	v_sub_f32_e32 v20, v100, v2
	v_mul_f32_e32 v20, 0x3fb8aa3b, v20
	v_exp_f32_e32 v148, v20
	v_sub_f32_e32 v20, v101, v2
	v_mul_f32_e32 v20, 0x3fb8aa3b, v20
	v_exp_f32_e32 v149, v20
	v_sub_f32_e32 v20, v86, v2
	v_mul_f32_e32 v20, 0x3fb8aa3b, v20
	v_exp_f32_e32 v152, v20
	v_sub_f32_e32 v20, v88, v2
	v_mul_f32_e32 v20, 0x3fb8aa3b, v20
	v_exp_f32_e32 v153, v20
	v_sub_f32_e32 v20, v90, v2
	v_mul_f32_e32 v20, 0x3fb8aa3b, v20
	v_exp_f32_e32 v154, v20
	v_sub_f32_e32 v20, v44, v2
	v_mul_f32_e32 v20, 0x3fb8aa3b, v20
	v_exp_f32_e32 v155, v20
	v_sub_f32_e32 v20, v92, v2
	v_mul_f32_e32 v20, 0x3fb8aa3b, v20
	v_exp_f32_e32 v156, v20
	v_sub_f32_e32 v20, v46, v2
	v_mul_f32_e32 v20, 0x3fb8aa3b, v20
	v_exp_f32_e32 v157, v20
	v_sub_f32_e32 v20, v42, v2
	v_mul_f32_e32 v20, 0x3fb8aa3b, v20
	v_exp_f32_e32 v158, v20
	v_sub_f32_e32 v20, v43, v2
	v_mul_f32_e32 v20, 0x3fb8aa3b, v20
	v_exp_f32_e32 v159, v20
	v_sub_f32_e32 v20, v87, v2
	v_mul_f32_e32 v20, 0x3fb8aa3b, v20
	v_exp_f32_e32 v160, v20
	v_sub_f32_e32 v20, v89, v2
	v_mul_f32_e32 v20, 0x3fb8aa3b, v20
	v_exp_f32_e32 v161, v20
	v_sub_f32_e32 v20, v91, v2
	v_mul_f32_e32 v20, 0x3fb8aa3b, v20
	v_exp_f32_e32 v162, v20
	v_sub_f32_e32 v20, v45, v2
	v_mul_f32_e32 v20, 0x3fb8aa3b, v20
	v_exp_f32_e32 v163, v20
	v_sub_f32_e32 v20, v93, v2
	v_mul_f32_e32 v20, 0x3fb8aa3b, v20
	v_exp_f32_e32 v164, v20
	v_sub_f32_e32 v20, v47, v2
	v_mul_f32_e32 v20, 0x3fb8aa3b, v20
	v_exp_f32_e32 v165, v20
	v_sub_f32_e32 v20, v94, v2
	v_mul_f32_e32 v20, 0x3fb8aa3b, v20
	v_exp_f32_e32 v166, v20
	v_sub_f32_e32 v20, v95, v2
	v_mul_f32_e32 v20, 0x3fb8aa3b, v20
	v_exp_f32_e32 v167, v20
	v_sub_f32_e32 v20, v107, v2
	v_mul_f32_e32 v20, 0x3fb8aa3b, v20
	v_exp_f32_e32 v168, v20
	v_sub_f32_e32 v20, v34, v2
	v_mul_f32_e32 v20, 0x3fb8aa3b, v20
	v_exp_f32_e32 v169, v20
	v_sub_f32_e32 v20, v36, v2
	v_sub_f32_e32 v3, v50, v2
	v_mul_f32_e32 v20, 0x3fb8aa3b, v20
	v_mul_f32_e32 v3, 0x3fb8aa3b, v3
	v_sub_f32_e32 v7, v114, v2
	v_exp_f32_e32 v170, v20
	v_sub_f32_e32 v20, v109, v2
	v_exp_f32_e32 v3, v3
	v_mul_f32_e32 v7, 0x3fb8aa3b, v7
	v_mul_f32_e32 v20, 0x3fb8aa3b, v20
	v_exp_f32_e32 v7, v7
	v_exp_f32_e32 v171, v20
	v_sub_f32_e32 v20, v38, v2
	v_mul_f32_e32 v20, 0x3fb8aa3b, v20
	v_exp_f32_e32 v172, v20
	v_sub_f32_e32 v20, v110, v2
	v_add_f32_e32 v19, 0, v3
	v_mul_f32_e32 v20, 0x3fb8aa3b, v20
	v_add_f32_e32 v19, v7, v19
	v_exp_f32_e32 v173, v20
	v_sub_f32_e32 v20, v40, v2
	v_add_f32_e32 v19, v115, v19
	v_mul_f32_e32 v20, 0x3fb8aa3b, v20
	v_add_f32_e32 v19, v118, v19
	v_exp_f32_e32 v174, v20
	v_sub_f32_e32 v20, v111, v2
	v_add_f32_e32 v19, v128, v19
	v_mul_f32_e32 v20, 0x3fb8aa3b, v20
	v_add_f32_e32 v19, v129, v19
	v_exp_f32_e32 v175, v20
	v_sub_f32_e32 v20, v123, v2
	v_add_lshl_u32 v50, s0, v252, 10
	v_add_f32_e32 v19, v130, v19
	v_mul_f32_e32 v24, 0x3fb8aa3b, v20
	v_lshl_add_u64 v[20:21], v[60:61], 0, v[50:51]
	v_sub_f32_e32 v28, v35, v2
	v_add_f32_e32 v19, v131, v19
	v_lshl_add_u64 v[150:151], s[70:71], 0, v[20:21]
	v_mul_f32_e32 v34, 0x3fb8aa3b, v28
	v_add_f32_e32 v19, v142, v19
	v_add_co_u32_e32 v32, vcc, s78, v150
	v_exp_f32_e32 v176, v34
	v_sub_f32_e32 v34, v37, v2
	v_add_f32_e32 v19, v143, v19
	v_addc_co_u32_e32 v33, vcc, 0, v151, vcc
	v_mul_f32_e32 v34, 0x3fb8aa3b, v34
	v_add_f32_e32 v19, v144, v19
	global_load_dwordx4 v[20:23], v[32:33], off
	v_exp_f32_e32 v50, v24
	global_load_dwordx4 v[24:27], v[32:33], off offset:256
	v_exp_f32_e32 v177, v34
	v_sub_f32_e32 v34, v124, v2
	v_add_co_u32_e32 v86, vcc, s79, v150
	v_add_f32_e32 v19, v145, v19
; __device__ __forceinline__ unsigned pk2(float lo, float hi) { unsigned r; asm("v_cvt_pk_bf16_f32 %0, %1, %2" : "=v"(r) : "v"(lo), "v"(hi)); return r; }
; __device__ __forceinline__ void na_phase(const Frame& F, const bf16* QH, const bf16* VB, const float* rpb, bf16* U) {
;     ...
;             float sum = 0.f;
; #pragma unroll
;             for (int blk = 0; blk < 16; ++blk)
; #pragma unroll
;                 for (int e = 0; e < 4; ++e) { const float p = __builtin_amdgcn_exp2f((acc[blk][e] - mx) * 1.44269504089f); acc[blk][e] = p; sum += p; }
;             sum += __shfl_xor(sum, 16); sum += __shfl_xor(sum, 32);
;             const float inv = 1.0f / sum;
;             f32x4 o[4];
; #pragma unroll
;             for (int db = 0; db < 4; ++db) o[db] = (f32x4){0.f, 0.f, 0.f, 0.f};
; #pragma unroll
;             for (int i = 0; i < 8; ++i) {
;                 v4u pw; pw.x = pk2(acc[2 * i][0], acc[2 * i][1]); pw.y = pk2(acc[2 * i][2], acc[2 * i][3]); pw.z = pk2(acc[2 * i + 1][0], acc[2 * i + 1][1]); pw.w = pk2(acc[2 * i + 1][2], acc[2 * i + 1][3]);
;                 const bf16x8 pf = __builtin_bit_cast(bf16x8, pw);
;                 const size_t vrow = (((size_t)h * 512 + b * 256 + rs + i) * 8 + (c0 >> 3) + q4) * 512;
; #pragma unroll
;                 for (int db = 0; db < 4; ++db) { const bf16x8 vfrag = *(const bf16x8*)(VB + vrow + (16 * db + n) * 8);
;                     o[db] = __builtin_amdgcn_mfma_f32_16x16x32_bf16(vfrag, pf, o[db], 0, 0, 0); }
;             }
	v_mul_f32_e32 v36, 0x3fb8aa3b, v34
	v_addc_co_u32_e32 v87, vcc, 0, v151, vcc
	v_add_f32_e32 v19, v146, v19
	global_load_dwordx4 v[28:31], v[32:33], off offset:512
	v_exp_f32_e32 v178, v36
	global_load_dwordx4 v[36:39], v[86:87], off
	v_sub_f32_e32 v44, v125, v2
	global_load_dwordx4 v[32:35], v[32:33], off offset:768
	v_add_f32_e32 v19, v147, v19
	v_mul_f32_e32 v44, 0x3fb8aa3b, v44
	v_add_f32_e32 v19, v148, v19
	global_load_dwordx4 v[40:43], v[86:87], off offset:256
	v_exp_f32_e32 v179, v44
	v_sub_f32_e32 v44, v126, v2
	v_sub_f32_e32 v88, v127, v2
	v_add_co_u32_e32 v102, vcc, s80, v150
	v_add_f32_e32 v19, v149, v19
	v_mul_f32_e32 v44, 0x3fb8aa3b, v44
	v_mul_f32_e32 v88, 0x3fb8aa3b, v88
	v_addc_co_u32_e32 v103, vcc, 0, v151, vcc
	v_add_f32_e32 v19, v152, v19
	v_exp_f32_e32 v180, v44
	global_load_dwordx4 v[44:47], v[86:87], off offset:512
	global_load_dwordx4 v[90:93], v[102:103], off
	v_exp_f32_e32 v181, v88
	global_load_dwordx4 v[86:89], v[86:87], off offset:768
	v_add_f32_e32 v19, v153, v19
	v_add_f32_e32 v19, v154, v19
	v_add_f32_e32 v19, v155, v19
	v_add_f32_e32 v19, v156, v19
	v_add_f32_e32 v19, v157, v19
	v_add_f32_e32 v19, v158, v19
	v_add_f32_e32 v19, v159, v19
	v_add_f32_e32 v19, v160, v19
	v_add_f32_e32 v19, v161, v19
	v_add_f32_e32 v19, v162, v19
	v_add_f32_e32 v19, v163, v19
	v_add_f32_e32 v19, v164, v19
	v_add_f32_e32 v19, v165, v19
	v_add_f32_e32 v19, v166, v19
	v_add_f32_e32 v19, v167, v19
	v_add_f32_e32 v19, v168, v19
	v_add_f32_e32 v19, v169, v19
	v_add_f32_e32 v19, v170, v19
	v_add_f32_e32 v19, v171, v19
	v_add_f32_e32 v19, v172, v19
	v_add_f32_e32 v19, v173, v19
	global_load_dwordx4 v[98:101], v[102:103], off offset:512
	v_add_f32_e32 v19, v174, v19
	v_add_f32_e32 v19, v175, v19
	v_add_f32_e32 v19, v50, v19
	v_add_f32_e32 v19, v176, v19
	v_sub_f32_e32 v94, v112, v2
	v_add_f32_e32 v19, v177, v19
	v_mul_f32_e32 v94, 0x3fb8aa3b, v94
	v_sub_f32_e32 v16, v16, v2
	v_add_f32_e32 v19, v178, v19
	v_exp_f32_e32 v182, v94
	v_mul_f32_e32 v16, 0x3fb8aa3b, v16
	v_add_f32_e32 v19, v179, v19
	global_load_dwordx4 v[94:97], v[102:103], off offset:256
	v_exp_f32_e32 v183, v16
	v_add_f32_e32 v19, v180, v19
	v_add_f32_e32 v19, v181, v19
	v_sub_f32_e32 v16, v17, v2
	v_sub_f32_e32 v107, v18, v2
	v_add_co_u32_e32 v116, vcc, s81, v150
	v_add_f32_e32 v106, v182, v19
	v_mul_f32_e32 v16, 0x3fb8aa3b, v16
	v_addc_co_u32_e32 v117, vcc, 0, v151, vcc
	v_mul_f32_e32 v107, 0x3fb8aa3b, v107
	v_exp_f32_e32 v184, v16
	global_load_dwordx4 v[16:19], v[116:117], off
	v_exp_f32_e32 v185, v107
	global_load_dwordx4 v[102:105], v[102:103], off offset:768
	v_add_f32_e32 v110, v183, v106
	global_load_dwordx4 v[106:109], v[116:117], off offset:256
	v_add_f32_e32 v110, v184, v110
	v_add_f32_e32 v132, v185, v110
	global_load_dwordx4 v[110:113], v[116:117], off offset:512
	v_cvt_pk_bf16_f32 v114, v3, v7
	v_cvt_pk_bf16_f32 v115, v115, v118
	global_load_dwordx4 v[118:121], v[116:117], off offset:768
	v_add_co_u32_e32 v134, vcc, s82, v150
	v_cvt_pk_bf16_f32 v116, v128, v129
	v_cvt_pk_bf16_f32 v117, v130, v131
	v_sub_f32_e32 v15, v15, v2
	s_waitcnt vmcnt(15)
	v_mfma_f32_16x16x32_bf16 v[20:23], v[20:23], v[114:117], 0
	v_addc_co_u32_e32 v135, vcc, 0, v151, vcc
	v_mul_f32_e32 v15, 0x3fb8aa3b, v15
	s_waitcnt vmcnt(14)
	v_mfma_f32_16x16x32_bf16 v[24:27], v[24:27], v[114:117], 0
	v_sub_f32_e32 v7, v14, v2
	v_add_co_u32_e32 v14, vcc, s83, v150
	s_waitcnt vmcnt(11)
	v_mfma_f32_16x16x32_bf16 v[32:35], v[32:35], v[114:117], 0
	v_exp_f32_e32 v186, v15
	v_addc_co_u32_e32 v15, vcc, 0, v151, vcc
	v_mfma_f32_16x16x32_bf16 v[28:31], v[28:31], v[114:117], 0
	global_load_dwordx4 v[138:141], v[14:15], off
	v_cvt_pk_bf16_f32 v114, v142, v143
	v_cvt_pk_bf16_f32 v115, v144, v145
	global_load_dwordx4 v[142:145], v[14:15], off offset:256
	v_cvt_pk_bf16_f32 v116, v146, v147
	v_cvt_pk_bf16_f32 v117, v148, v149
	global_load_dwordx4 v[122:125], v[134:135], off
	global_load_dwordx4 v[126:129], v[134:135], off offset:256
	v_mfma_f32_16x16x32_bf16 v[20:23], v[36:39], v[114:117], v[20:23]
	global_load_dwordx4 v[36:39], v[14:15], off offset:512
	v_add_f32_e32 v3, v186, v132
	global_load_dwordx4 v[130:133], v[134:135], off offset:512
	s_waitcnt vmcnt(16)
	v_mfma_f32_16x16x32_bf16 v[24:27], v[40:43], v[114:117], v[24:27]
	global_load_dwordx4 v[40:43], v[14:15], off offset:768
	v_add_co_u32_e32 v14, vcc, s84, v150
	s_waitcnt vmcnt(14)
	v_mfma_f32_16x16x32_bf16 v[32:35], v[86:89], v[114:117], v[32:35]
	v_addc_co_u32_e32 v15, vcc, 0, v151, vcc
	v_cvt_pk_bf16_f32 v87, v154, v155
	v_add_co_u32_e32 v154, vcc, s85, v150
	v_cvt_pk_bf16_f32 v86, v152, v153
	global_load_dwordx4 v[146:149], v[14:15], off
	s_nop 0
	v_addc_co_u32_e32 v155, vcc, 0, v151, vcc
	global_load_dwordx4 v[150:153], v[154:155], off
	v_mfma_f32_16x16x32_bf16 v[28:31], v[44:47], v[114:117], v[28:31]
	global_load_dwordx4 v[134:137], v[134:135], off offset:768
	v_cvt_pk_bf16_f32 v88, v156, v157
	global_load_dwordx4 v[44:47], v[14:15], off offset:256
	global_load_dwordx4 v[114:117], v[14:15], off offset:512
	v_cvt_pk_bf16_f32 v89, v158, v159
	v_mul_f32_e32 v7, 0x3fb8aa3b, v7
	v_mfma_f32_16x16x32_bf16 v[20:23], v[90:93], v[86:89], v[20:23]
	global_load_dwordx4 v[90:93], v[14:15], off offset:768
	v_exp_f32_e32 v187, v7
	v_sub_f32_e32 v7, v13, v2
	v_mul_f32_e32 v7, 0x3fb8aa3b, v7
	v_exp_f32_e32 v188, v7
	v_sub_f32_e32 v7, v12, v2
	s_waitcnt vmcnt(19)
; __device__ __forceinline__ unsigned pk2(float lo, float hi) { unsigned r; asm("v_cvt_pk_bf16_f32 %0, %1, %2" : "=v"(r) : "v"(lo), "v"(hi)); return r; }
; __device__ __forceinline__ void na_phase(const Frame& F, const bf16* QH, const bf16* VB, const float* rpb, bf16* U) {
;     ...
;             sum += __shfl_xor(sum, 16); sum += __shfl_xor(sum, 32);
;             const float inv = 1.0f / sum;
;             f32x4 o[4];
; #pragma unroll
;             for (int db = 0; db < 4; ++db) o[db] = (f32x4){0.f, 0.f, 0.f, 0.f};
; #pragma unroll
;             for (int i = 0; i < 8; ++i) {
;                 v4u pw; pw.x = pk2(acc[2 * i][0], acc[2 * i][1]); pw.y = pk2(acc[2 * i][2], acc[2 * i][3]); pw.z = pk2(acc[2 * i + 1][0], acc[2 * i + 1][1]); pw.w = pk2(acc[2 * i + 1][2], acc[2 * i + 1][3]);
;                 const bf16x8 pf = __builtin_bit_cast(bf16x8, pw);
;                 const size_t vrow = (((size_t)h * 512 + b * 256 + rs + i) * 8 + (c0 >> 3) + q4) * 512;
; #pragma unroll
;                 for (int db = 0; db < 4; ++db) { const bf16x8 vfrag = *(const bf16x8*)(VB + vrow + (16 * db + n) * 8);
;                     o[db] = __builtin_amdgcn_mfma_f32_16x16x32_bf16(vfrag, pf, o[db], 0, 0, 0); }
;             }
; #pragma unroll
;             for (int db = 0; db < 4; ++db) { v2u w; w.x = pk2(o[db][0] * inv, o[db][1] * inv); w.y = pk2(o[db][2] * inv, o[db][3] * inv);
;                 *(v2u*)(U + tokq * DM + h * 64 + 16 * db + 4 * q4) = w; }
	v_mfma_f32_16x16x32_bf16 v[12:15], v[98:101], v[86:89], v[28:31]
	v_mul_f32_e32 v7, 0x3fb8aa3b, v7
	v_exp_f32_e32 v156, v7
	v_sub_f32_e32 v7, v11, v2
	global_load_dwordx4 v[28:31], v[154:155], off offset:256
	s_waitcnt vmcnt(19)
	v_mfma_f32_16x16x32_bf16 v[24:27], v[94:97], v[86:89], v[24:27]
	global_load_dwordx4 v[94:97], v[154:155], off offset:512
	v_mul_f32_e32 v7, 0x3fb8aa3b, v7
	v_exp_f32_e32 v98, v7
	s_waitcnt vmcnt(18)
	v_mfma_f32_16x16x32_bf16 v[32:35], v[102:105], v[86:89], v[32:35]
	v_cvt_pk_bf16_f32 v86, v160, v161
	v_cvt_pk_bf16_f32 v87, v162, v163
	v_cvt_pk_bf16_f32 v88, v164, v165
	v_cvt_pk_bf16_f32 v89, v166, v167
	v_sub_f32_e32 v7, v10, v2
	v_mfma_f32_16x16x32_bf16 v[16:19], v[16:19], v[86:89], v[20:23]
	v_mul_f32_e32 v7, 0x3fb8aa3b, v7
	v_exp_f32_e32 v99, v7
	v_sub_f32_e32 v7, v9, v2
	s_waitcnt vmcnt(17)
	v_mfma_f32_16x16x32_bf16 v[20:23], v[106:109], v[86:89], v[24:27]
	v_mul_f32_e32 v7, 0x3fb8aa3b, v7
	v_add_f32_e32 v3, v187, v3
	v_exp_f32_e32 v100, v7
	global_load_dwordx4 v[24:27], v[154:155], off offset:768
	s_waitcnt vmcnt(17)
	v_mfma_f32_16x16x32_bf16 v[10:13], v[110:113], v[86:89], v[12:15]
	v_sub_f32_e32 v7, v8, v2
	v_add_f32_e32 v3, v188, v3
	v_mul_f32_e32 v7, 0x3fb8aa3b, v7
	s_waitcnt vmcnt(16)
	v_mfma_f32_16x16x32_bf16 v[32:35], v[118:121], v[86:89], v[32:35]
	v_sub_f32_e32 v6, v6, v2
	v_add_f32_e32 v3, v156, v3
	v_exp_f32_e32 v101, v7
	v_mul_f32_e32 v6, 0x3fb8aa3b, v6
	v_sub_f32_e32 v5, v5, v2
	v_cvt_pk_bf16_f32 v86, v168, v169
	v_add_f32_e32 v3, v98, v3
	v_exp_f32_e32 v102, v6
	v_mul_f32_e32 v5, 0x3fb8aa3b, v5
	v_cvt_pk_bf16_f32 v87, v170, v171
	v_cvt_pk_bf16_f32 v88, v172, v173
	v_cvt_pk_bf16_f32 v89, v174, v175
	v_add_f32_e32 v3, v99, v3
	s_waitcnt vmcnt(13)
	v_mfma_f32_16x16x32_bf16 v[14:17], v[122:125], v[86:89], v[16:19]
	v_add_f32_e32 v3, v100, v3
	v_add_f32_e32 v3, v101, v3
	v_add_f32_e32 v3, v102, v3
	s_waitcnt vmcnt(12)
	v_mfma_f32_16x16x32_bf16 v[18:21], v[126:129], v[86:89], v[20:23]
	v_sub_f32_e32 v1, v1, v2
	v_mul_f32_e32 v1, 0x3fb8aa3b, v1
	v_sub_f32_e32 v0, v0, v2
	s_waitcnt vmcnt(10)
	v_mfma_f32_16x16x32_bf16 v[8:11], v[130:133], v[86:89], v[10:13]
	v_mul_f32_e32 v0, 0x3fb8aa3b, v0
	v_lshl_add_u64 v[60:61], v[60:61], 0, s[48:49]
	s_waitcnt vmcnt(6)
	v_mfma_f32_16x16x32_bf16 v[32:35], v[134:137], v[86:89], v[32:35]
	v_cvt_pk_bf16_f32 v86, v50, v176
	v_exp_f32_e32 v50, v5
	v_cvt_pk_bf16_f32 v87, v177, v178
	v_cvt_pk_bf16_f32 v88, v179, v180
	v_cvt_pk_bf16_f32 v89, v181, v182
	s_nop 0
	v_add_f32_e32 v5, v50, v3
	v_sub_f32_e32 v3, v4, v2
	v_mfma_f32_16x16x32_bf16 v[12:15], v[138:141], v[86:89], v[14:17]
	v_mul_f32_e32 v3, 0x3fb8aa3b, v3
	v_mfma_f32_16x16x32_bf16 v[6:9], v[36:39], v[86:89], v[8:11]
	v_exp_f32_e32 v36, v3
	v_exp_f32_e32 v37, v1
	v_exp_f32_e32 v38, v0
	v_mfma_f32_16x16x32_bf16 v[16:19], v[142:145], v[86:89], v[18:21]
	v_add_f32_e32 v4, v36, v5
	v_add_f32_e32 v4, v37, v4
	v_add_f32_e32 v39, v38, v4
	v_mfma_f32_16x16x32_bf16 v[20:23], v[40:43], v[86:89], v[32:35]
	v_cvt_pk_bf16_f32 v32, v183, v184
	v_cvt_pk_bf16_f32 v33, v185, v186
	v_cvt_pk_bf16_f32 v34, v187, v188
	v_cvt_pk_bf16_f32 v35, v156, v98
	s_nop 0
	v_mfma_f32_16x16x32_bf16 v[10:13], v[146:149], v[32:35], v[12:15]
	s_waitcnt vmcnt(5)
	v_mfma_f32_16x16x32_bf16 v[14:17], v[44:47], v[32:35], v[16:19]
	v_cvt_pk_bf16_f32 v18, v99, v100
	v_cvt_pk_bf16_f32 v19, v101, v102
	s_waitcnt vmcnt(4)
	v_mfma_f32_16x16x32_bf16 v[0:3], v[114:117], v[32:35], v[6:9]
	s_waitcnt vmcnt(3)
	v_mfma_f32_16x16x32_bf16 v[4:7], v[90:93], v[32:35], v[20:23]
	v_cvt_pk_bf16_f32 v20, v50, v36
	v_cvt_pk_bf16_f32 v21, v37, v38
	s_nop 0
	v_mfma_f32_16x16x32_bf16 v[8:11], v[150:153], v[18:21], v[10:13]
	s_nop 2
	ds_bpermute_b32 v12, v73, v39
	s_waitcnt vmcnt(1)
	v_mfma_f32_16x16x32_bf16 v[0:3], v[94:97], v[18:21], v[0:3]
	s_waitcnt lgkmcnt(0)
	v_add_f32_e32 v22, v39, v12
	v_mfma_f32_16x16x32_bf16 v[12:15], v[28:31], v[18:21], v[14:17]
	s_nop 2
	ds_bpermute_b32 v16, v74, v22
	s_waitcnt vmcnt(0)
	v_mfma_f32_16x16x32_bf16 v[4:7], v[24:27], v[18:21], v[4:7]
	s_waitcnt lgkmcnt(0)
	v_add_f32_e32 v16, v22, v16
	v_div_scale_f32 v17, s[0:1], v16, v16, 1.0
	v_rcp_f32_e32 v22, v17
	s_nop 0
	v_fma_f32 v18, -v17, v22, 1.0
	v_fmac_f32_e32 v22, v18, v22
	v_div_scale_f32 v18, vcc, 1.0, v16, 1.0
	v_mul_f32_e32 v19, v18, v22
	v_fma_f32 v20, -v17, v19, v18
	v_fmac_f32_e32 v19, v20, v22
	v_fma_f32 v17, -v17, v19, v18
	v_div_fmas_f32 v17, v17, v22, v19
	v_div_fixup_f32 v18, v17, v16, 1.0
	v_mul_f32_e32 v8, v18, v8
	v_mul_f32_e32 v9, v18, v9
	v_mul_f32_e32 v0, v18, v0
	v_mul_f32_e32 v1, v18, v1
	v_cvt_pk_bf16_f32 v8, v8, v9
	v_mul_f32_e32 v9, v18, v10
	v_cvt_pk_bf16_f32 v0, v0, v1
	v_mul_f32_e32 v1, v18, v2
	v_lshl_add_u64 v[16:17], s[70:71], 0, v[62:63]
	v_mul_f32_e32 v10, v18, v11
	v_cvt_pk_bf16_f32 v9, v9, v10
	v_mul_f32_e32 v2, v18, v3
	v_cvt_pk_bf16_f32 v1, v1, v2
	global_store_dwordx2 v[16:17], v[8:9], off offset:-64
	v_mul_f32_e32 v8, v18, v12
	v_mul_f32_e32 v9, v18, v13
	global_store_dwordx2 v[16:17], v[0:1], off
	v_mul_f32_e32 v0, v18, v4
	v_mul_f32_e32 v1, v18, v5
	v_cvt_pk_bf16_f32 v8, v8, v9
	v_mul_f32_e32 v9, v18, v14
	v_cvt_pk_bf16_f32 v0, v0, v1
	v_mul_f32_e32 v1, v18, v6
	v_lshl_add_u64 v[62:63], v[62:63], 0, s[50:51]
	v_mul_f32_e32 v10, v18, v15
	v_cvt_pk_bf16_f32 v9, v9, v10
	global_store_dwordx2 v[16:17], v[8:9], off offset:-32
	v_mul_f32_e32 v2, v18, v7
	v_cvt_pk_bf16_f32 v1, v1, v2
	global_store_dwordx2 v[16:17], v[0:1], off offset:32
	s_cbranch_scc1 .LBB0_904
